# GLA scan: transposed output product so each lane stores 16-byte rows (2 stores per wave per chunk instead of 16), conflict-free swizzles for transposed reads
# speedup vs baseline: 1.0297x; 1.0045x over previous
; __device__ __forceinline__ void gla_scan_phase(const Params& p, int j, bool need_ctx, char* smem, int tid, int bid) {
;     ...
;   for (int unit = bid; unit < 256; unit += gridDim.x) {
;     int dir, dvs, h, b;
;     if (gridDim.x == 256) { const int g = (unit & 7) * 8 + (unit >> 5); dvs = (unit >> 3) & 3; dir = g & 1; h = (g >> 1) & 3; b = g >> 3; }
;     else { dir = unit & 1; dvs = (unit >> 1) & 3; h = (unit >> 3) & 3; b = unit >> 5; }
;     const int dvc = tid & 63, tg = tid >> 6;
;     f32x16 Sacc;
; #pragma unroll
;     for (int r = 0; r < 16; ++r) Sacc[r] = 0.f;
;     __syncthreads();
;     { u32x4 z = {0u, 0u, 0u, 0u}; *(u32x4*)(STL + tid * 32) = z; *(u32x4*)(STL + tid * 32 + 16) = z; }
;     u32x4 qx[2], kx[2]; unsigned kt[16], vv[8]; float ebv = 0.f;
;     const u16* QB = (const u16*)(p.ws + OFF_GQB);
;     const u16* KB2 = (const u16*)((const char*)p.out + OUT_GKB);
;     const float* EBE = (const float*)((const char*)p.out + OUT_EBE);
;     const u16* qsrc = dir ? QB + h * 128 : P + h * 128;
;     const u16* ksrc = dir ? KB2 + h * 128 : P + 512 + h * 128;
;     const long rst = dir ? 512 : LDP;
;     const long sgn = dir ? -1 : 1;
.Lgs_map_done:
	v_readlane_b32 s0, v253, 28
	v_readlane_b32 s1, v253, 29
	v_readlane_b32 s4, v253, 43
	v_readlane_b32 s5, v253, 44
	v_readlane_b32 s8, v253, 45
	v_readlane_b32 s9, v253, 46
	v_readlane_b32 s10, v253, 47
	v_readlane_b32 s11, v253, 48
	v_readlane_b32 s18, v253, 41
	v_readlane_b32 s19, v253, 42
	s_movk_i32 s16, 0x400
	s_cmp_eq_u32 s55, 0
	s_cselect_b32 s34, 0x1840, s16
	s_cselect_b32 s80, 0, 63
	s_cselect_b32 s22, s92, s0
	s_cselect_b32 s23, s93, s1
	s_cselect_b32 s24, s4, s8
	s_cselect_b32 s25, s5, s9
	s_cselect_b32 s30, s12, s18
	s_cselect_b32 s31, s13, s19
	s_lshl_b32 s16, s73, 8
	s_add_u32 s22, s22, s16
	s_addc_u32 s23, s23, 0
	s_add_u32 s24, s24, s16
	s_addc_u32 s25, s25, 0
	s_lshl_b32 s0, s73, 9
	s_lshl_b32 s1, s72, 7
	s_add_u32 s0, s0, s1
	s_add_u32 s30, s30, s0
	s_addc_u32 s31, s31, 0
	s_add_u32 s0, s0, 0x800
	s_add_u32 s26, s92, s0
	s_addc_u32 s27, s93, 0
	s_mul_i32 s4, s55, 0x110000
	s_lshl_b32 s5, s73, 9
	s_add_u32 s4, s4, s5
	s_add_u32 s28, s10, s4
	s_addc_u32 s29, s11, 0
	v_and_b32_e32 v100, 63, v203
	v_lshrrev_b32_e32 v101, 6, v203
	v_and_b32_e32 v102, 31, v203
	v_bfe_u32 v103, v203, 5, 1
	v_and_b32_e32 v104, 15, v203
	v_bfe_u32 v105, v203, 1, 3
	v_readfirstlane_b32 s0, v101
	s_mov_b32 s81, s0
	s_lshr_b32 s1, s0, 1
	s_and_b32 s77, s1, 1
	s_and_b32 s4, s0, 1
	s_cmp_gt_u32 s0, 3
	s_cselect_b32 s76, 2, 0
	s_cmp_eq_u32 s0, 1
	s_cselect_b32 s76, 1, s76
	s_lshl_b32 s5, s4, 13
	s_lshl_b32 s8, s77, 13
	s_add_u32 s9, s5, 0x4000
	s_add_u32 s10, s5, 0x12000
	s_cmp_eq_u32 s76, 2
	s_cselect_b32 s72, s10, s9
	s_cselect_b32 s73, s8, s8
	v_xor_b32_e32 v107, v103, v104
	v_lshlrev_b32_e32 v107, 4, v107
	v_lshl_or_b32 v107, v102, 8, v107
	v_add_u32_e32 v108, s72, v107
	v_add_u32_e32 v109, s73, v107
	s_cmp_eq_u32 s76, 2
	s_cbranch_scc1 .Lgs_akf_done
	v_and_b32_e32 v198, 3, v102
	v_bfe_u32 v199, v102, 2, 2
	v_lshl_or_b32 v198, v198, 2, v199
	v_xor_b32_e32 v198, v103, v198
	v_lshlrev_b32_e32 v198, 4, v198
	v_lshl_or_b32 v198, v102, 8, v198
	v_add_u32_e32 v108, s72, v198
.Lgs_akf_done:
	v_mov_b32_e32 v220, v108
	v_mov_b32_e32 v228, v109
	v_xor_b32_e32 v107, v103, v105
	v_lshlrev_b32_e32 v107, 4, v107
	v_lshl_or_b32 v107, v102, 7, v107
	s_lshl_b32 s9, s77, 12
	s_add_u32 s9, s9, 0x10000
	v_add_u32_e32 v249, s9, v107
	s_lshl_b32 s8, s4, 2
	v_xor_b32_e32 v108, s8, v105
	v_lshlrev_b32_e32 v108, 4, v108
	v_lshl_or_b32 v108, v102, 7, v108
	v_lshl_or_b32 v108, v103, 3, v108
	v_add_u32_e32 v108, s9, v108
	s_cmp_eq_u32 s76, 2
	s_cbranch_scc1 .Lgs_sclw_done
	v_mov_b32_e32 v249, v108
.Lgs_sclw_done:
	s_lshl_b32 s8, s1, 2
	v_xor_b32_e32 v108, s8, v104
	v_lshlrev_b32_e32 v108, 4, v108
	v_lshl_or_b32 v108, v102, 8, v108
	v_lshl_or_b32 v108, v103, 3, v108
	s_add_u32 s9, s5, 0x12000
	v_add_u32_e32 v250, s9, v108
	s_lshl_b32 s9, s1, 7
	s_add_u32 s9, s9, 0x16000
	v_lshlrev_b32_e32 v108, 4, v103
	v_add_u32_e32 v252, s9, v108
	v_lshrrev_b32_e32 v106, 3, v203
	v_and_b32_e32 v107, 7, v203
	v_and_b32_e32 v108, 15, v106
	v_xor_b32_e32 v108, v107, v108
	v_lshlrev_b32_e32 v108, 4, v108
	v_lshl_or_b32 v192, v106, 8, v108
	v_xor_b32_e32 v193, 0x80, v192
	v_and_b32_e32 v198, 3, v106
	v_bfe_u32 v199, v106, 2, 2
	v_lshl_or_b32 v198, v198, 2, v199
	v_xor_b32_e32 v198, v107, v198
	v_lshlrev_b32_e32 v198, 4, v198
	v_lshl_or_b32 v143, v106, 8, v198
	v_xor_b32_e32 v144, 0x80, v143
	v_bfe_u32 v198, v106, 1, 1
	v_lshlrev_b32_e32 v198, 2, v198
	v_xor_b32_e32 v198, v107, v198
	v_lshlrev_b32_e32 v198, 4, v198
	v_lshl_or_b32 v196, v106, 7, v198
	v_add_u32_e32 v196, 0xc000, v196
	v_bfe_u32 v108, v203, 4, 1
	v_bfe_u32 v109, v203, 2, 2
	v_and_b32_e32 v198, 3, v203
	v_lshrrev_b32_e32 v199, 1, v198
	v_lshl_or_b32 v199, v108, 1, v199
	v_and_b32_e32 v198, 1, v198
	v_lshlrev_b32_e32 v198, 3, v198
	v_lshl_or_b32 v109, v103, 3, v109
	s_lshl_b32 s9, s1, 2
	v_or_b32_e32 v200, s9, v199
	v_add_u32_e32 v153, 0, v109
	v_and_b32_e32 v140, 3, v153
	v_bfe_u32 v108, v153, 2, 2
	v_lshl_or_b32 v140, v140, 2, v108
	v_xor_b32_e32 v140, v200, v140
	v_lshlrev_b32_e32 v140, 4, v140
	v_lshl_or_b32 v140, v153, 8, v140
	v_or_b32_e32 v140, v140, v198
	v_add_u32_e32 v153, 4, v109
	v_and_b32_e32 v141, 3, v153
	v_bfe_u32 v108, v153, 2, 2
	v_lshl_or_b32 v141, v141, 2, v108
	v_xor_b32_e32 v141, v200, v141
	v_lshlrev_b32_e32 v141, 4, v141
	v_lshl_or_b32 v141, v153, 8, v141
	v_or_b32_e32 v141, v141, v198
	s_lshl_b32 s9, s4, 2
	v_or_b32_e32 v200, s9, v199
	v_bfe_u32 v108, v109, 1, 1
	v_lshlrev_b32_e32 v108, 2, v108
	v_xor_b32_e32 v200, v200, v108
	v_lshlrev_b32_e32 v142, 4, v200
	v_lshl_or_b32 v142, v109, 7, v142
	v_or_b32_e32 v142, v142, v198
	v_lshlrev_b32_e32 v191, 2, v203
	v_add_u32_e32 v197, 0x16000, v191
	v_xor_b32_e32 v198, s80, v106
	v_mul_lo_u32 v198, v198, s34
	v_lshl_add_u32 v166, v107, 4, v198
	s_movk_i32 s9, 0x1840
	v_xor_b32_e32 v198, s80, v106
	v_mul_lo_u32 v198, v198, s9
	v_lshl_add_u32 v183, v107, 4, v198
	s_cmp_eq_u32 s76, 2
	s_cbranch_scc0 .Lgs_masks
	s_lshl_b32 s9, s77, 5
	v_add_u32_e32 v198, s9, v102
	v_xor_b32_e32 v198, s80, v198
	s_lshl_b32 s9, s4, 6
	v_lshl_add_u32 v108, v103, 4, s9
	v_lshl_add_u32 v204, v198, 11, v108
	s_branch .Lgs_roles_done

; __device__ __forceinline__ void gla_scan_phase(const Params& p, int j, bool need_ctx, char* smem, int tid, int bid) {
;     ...
;     for (int ci = 0; ci < 68; ++ci) {
;       asm volatile("" : "+v"(tid));
;       const int lane = tid & 63, wid = tid >> 6, l32 = lane & 31, hi = lane >> 5;
;       const int tbg = wid >> 2, kd = (wid & 3) * 32 + l32;
;       const int dvc = tid & 63, tg = tid >> 6;
;       const bool is_ctx = ci < 4; const int c = is_ctx ? ci : ci - 4; const int TT = is_ctx ? CTXL : SEQL;
;       const int base = is_ctx ? ML + b * CTXL : b * SEQL;
;       char* vT = vT0 + (ci & 1) * 40960;
;       {
.Lgs_pair:
.Lgs0_chunk:
	s_add_i32 s1, s54, -4
	s_cmp_lt_u32 s54, 4
	s_cselect_b32 s0, s54, s1
	s_movk_i32 s5, 0x1000
	s_cselect_b32 s1, 0x100, s5
	s_lshl_b32 s4, s35, 8
	s_add_u32 s4, s4, 0x8000
	s_lshl_b32 s5, s35, 12
	s_cmp_lt_u32 s54, 4
	s_cselect_b32 s4, s4, s5
	s_lshl_b32 s0, s0, 6
	s_sub_u32 s1, s1, 64
	s_sub_u32 s1, s1, s0
	s_cmp_eq_u32 s55, 0
	s_cselect_b32 s0, s0, s1
	s_add_u32 s0, s4, s0
	s_lshl_b32 s1, s0, 11
	s_add_u32 s20, s30, s1
	s_addc_u32 s21, s31, 0
	s_cmp_gt_u32 s54, 3
	s_cselect_b32 s96, 1, s60
	s_add_u32 s0, s97, s16
	s_cmp_eq_u32 s0, 0
	s_cbranch_scc1 .Lgs0_w29
	s_cmp_eq_u32 s0, 2
	s_cbranch_scc1 .Lgs0_w45
	s_waitcnt vmcnt(10)
	s_branch .Lgs0_waited
.Lgs0_w45:
	s_waitcnt vmcnt(8)
	s_branch .Lgs0_waited

; __device__ __forceinline__ void gla_scan_phase(const Params& p, int j, bool need_ctx, char* smem, int tid, int bid) {
;     ...
;       {
;         if (tid < 128) ebend[tid] = ebv;
;         const int r = tid >> 3, c0 = tid & 7;
;         *(u32x4*)(qbL + swz256(r, c0)) = qx[0]; *(u32x4*)(qbL + swz256(r, c0 + 8)) = qx[1];
;         *(u32x4*)(kinvL + swz256(r, c0)) = kx[0]; *(u32x4*)(kinvL + swz256(r, c0 + 8)) = kx[1];
;         const int kdt = tid & 127, tgk = tid >> 7;
;         u32x4 w0 = {kt[0] | (kt[1] << 16), kt[2] | (kt[3] << 16), kt[4] | (kt[5] << 16), kt[6] | (kt[7] << 16)};
;         u32x4 w1 = {kt[8] | (kt[9] << 16), kt[10] | (kt[11] << 16), kt[12] | (kt[13] << 16), kt[14] | (kt[15] << 16)};
;         *(u32x4*)(kendT + swz128(kdt, tgk)) = w0;
;         *(u32x4*)(kendT + swz128(kdt, tgk + 4)) = w1;
;         u32x4 wv = {vv[0] | (vv[1] << 16), vv[2] | (vv[3] << 16), vv[4] | (vv[5] << 16), vv[6] | (vv[7] << 16)};
;         *(u32x4*)(vT + swz128(dvc, tg)) = wv;
;       }
.Lgs0_waited:
	ds_write_b128 v192, v[112:115]
	ds_write_b128 v193, v[116:119]
	ds_write_b128 v143, v[120:123] offset:16384
	ds_write_b128 v144, v[124:127] offset:16384
	ds_write_b128 v196, v[128:131]
	s_cmp_gt_u32 s81, 1
	s_cbranch_scc1 .Lgs0_noeb
	ds_write_b32 v197, v132

; __device__ __forceinline__ u16 f2bf(float x) { return (u16)(cvtpk(x, 0.f) & 0xffffu); }
; __device__ __forceinline__ int crow(int r, int hi) { return (r & 3) + 8 * (r >> 2) + 4 * hi; }
; __device__ __forceinline__ void gla_scan_phase(const Params& p, int j, bool need_ctx, char* smem, int tid, int bid) {
;     ...
;           Sacc[rg * 4 + 0] *= e4[0]; Sacc[rg * 4 + 1] *= e4[1]; Sacc[rg * 4 + 2] *= e4[2]; Sacc[rg * 4 + 3] *= e4[3];
;         }
;       }
;       __syncthreads();
;       if (wid >= 4 && need_o) {
; #pragma unroll
;         for (int k16 = 0; k16 < 4; ++k16) {
;           if (k16 < 2 || tbo == 1) {
;             const bf16x8 a = *(const bf16x8*)(scL + swz128(tbo * 32 + l32, k16 * 2 + hi));
;             const bf16x8 bv = *(const bf16x8*)(vT + swz128(dvbo * 32 + l32, k16 * 2 + hi));
;             oacc = __builtin_amdgcn_mfma_f32_32x32x16_bf16(a, bv, oacc, 0, 0, 0);
;           }
;         }
;         if (!is_ctx || need_ctx) {
;           u16* O = dir ? OB : OF;
; #pragma unroll
;           for (int r = 0; r < 16; ++r) {
;             const int pos = c * 64 + tbo * 32 + crow(r, hi);
;             const int tok = dir ? TT - 1 - pos : pos;
;             O[(size_t)(base + tok) * 1024 + h * 256 + dvs * 64 + dvbo * 32 + l32] = f2bf(oacc[r]);
;           }
;         }
;       }
;       {
;         const int dv = dvb2 * 32 + l32;
; #pragma unroll
;         for (int rg = 0; rg < 4; ++rg) {
;           const int k0 = kb * 32 + 8 * rg + 4 * hi;
;           u32x2 w = {cvtpk(Sacc[rg * 4 + 0], Sacc[rg * 4 + 1]), cvtpk(Sacc[rg * 4 + 2], Sacc[rg * 4 + 3])};
;           *(u32x2*)(STL + swz256(dv, k0 >> 3) + (k0 & 7) * 2) = w;
;         }
;       }
.Lgs0_noscore:
	s_nop 7
	s_nop 3
	s_waitcnt lgkmcnt(0)
	v_mul_f32_e32 v0, v0, v48
	v_mul_f32_e32 v1, v1, v49
	v_mul_f32_e32 v2, v2, v50
	v_mul_f32_e32 v3, v3, v51
	v_mul_f32_e32 v4, v4, v52
	v_mul_f32_e32 v5, v5, v53
	v_mul_f32_e32 v6, v6, v54
	v_mul_f32_e32 v7, v7, v55
	v_mul_f32_e32 v8, v8, v56
	v_mul_f32_e32 v9, v9, v57
	v_mul_f32_e32 v10, v10, v58
	v_mul_f32_e32 v11, v11, v59
	v_mul_f32_e32 v12, v12, v60
	v_mul_f32_e32 v13, v13, v61
	v_mul_f32_e32 v14, v14, v62
	v_mul_f32_e32 v15, v15, v63
	s_barrier
	s_mov_b32 s16, s97
	s_mov_b32 s97, 0
	s_cmp_eq_u32 s96, 0
	s_cbranch_scc1 .Lgs0_state
	s_cmp_eq_u32 s76, 2
	s_cbranch_scc0 .Lgs0_state
	v_xor_b32_e32 v198, 32, v249
	ds_read_b128 v[32:35], v249
	ds_read_b128 v[36:39], v198
	s_cmp_eq_u32 s77, 0
	s_cbranch_scc1 .Lgs0_ohalf
	v_xor_b32_e32 v199, 64, v249
	v_xor_b32_e32 v200, 96, v249
	ds_read_b128 v[40:43], v199
	ds_read_b128 v[44:47], v200
	s_waitcnt lgkmcnt(2)
	v_mfma_f32_32x32x16_bf16 v[16:31], v[80:83], v[32:35], v[16:31]
	v_mfma_f32_32x32x16_bf16 v[16:31], v[84:87], v[36:39], v[16:31]
	s_waitcnt lgkmcnt(0)
	v_mfma_f32_32x32x16_bf16 v[16:31], v[88:91], v[40:43], v[16:31]
	v_mfma_f32_32x32x16_bf16 v[16:31], v[92:95], v[44:47], v[16:31]
	s_branch .Lgs0_ostore
.Lgs0_ohalf:
	s_waitcnt lgkmcnt(0)
	v_mfma_f32_32x32x16_bf16 v[16:31], v[80:83], v[32:35], v[16:31]
	v_mfma_f32_32x32x16_bf16 v[16:31], v[84:87], v[36:39], v[16:31]
.Lgs0_ostore:
	v_cvt_pk_bf16_f32 v48, v0, v1
	v_cvt_pk_bf16_f32 v49, v2, v3
	v_cvt_pk_bf16_f32 v50, v4, v5
	v_cvt_pk_bf16_f32 v51, v6, v7
	v_cvt_pk_bf16_f32 v52, v8, v9
	v_cvt_pk_bf16_f32 v53, v10, v11
	v_cvt_pk_bf16_f32 v54, v12, v13
	v_cvt_pk_bf16_f32 v55, v14, v15
	v_xor_b32_e32 v198, 16, v250
	v_xor_b32_e32 v199, 32, v250
	v_xor_b32_e32 v200, 48, v250
	ds_write_b64 v250, v[48:49]
	ds_write_b64 v198, v[50:51]
	ds_write_b64 v199, v[52:53]
	ds_write_b64 v200, v[54:55]
	s_nop 3
	v_cvt_pk_bf16_f32 v32, v16, v17
	v_cvt_pk_bf16_f32 v33, v18, v19
	v_cvt_pk_bf16_f32 v34, v20, v21
	v_cvt_pk_bf16_f32 v35, v22, v23
	v_cvt_pk_bf16_f32 v36, v24, v25
	v_cvt_pk_bf16_f32 v37, v26, v27
	v_cvt_pk_bf16_f32 v38, v28, v29
	v_cvt_pk_bf16_f32 v39, v30, v31
	s_nop 0
	v_permlane32_swap_b32_e32 v32, v34
	v_permlane32_swap_b32_e32 v33, v35
	v_permlane32_swap_b32_e32 v36, v38
	v_permlane32_swap_b32_e32 v37, v39
	global_store_dwordx4 v204, v[32:35], s[20:21]
	global_store_dwordx4 v204, v[36:39], s[20:21] offset:32
	s_mov_b32 s97, 2
	s_branch .Lgs0_next

; __device__ __forceinline__ void gla_scan_phase(const Params& p, int j, bool need_ctx, char* smem, int tid, int bid) {
;     ...
;     for (int ci = 0; ci < 68; ++ci) {
;       asm volatile("" : "+v"(tid));
;       const int lane = tid & 63, wid = tid >> 6, l32 = lane & 31, hi = lane >> 5;
;       const int tbg = wid >> 2, kd = (wid & 3) * 32 + l32;
;       const int dvc = tid & 63, tg = tid >> 6;
;       const bool is_ctx = ci < 4; const int c = is_ctx ? ci : ci - 4; const int TT = is_ctx ? CTXL : SEQL;
;       const int base = is_ctx ? ML + b * CTXL : b * SEQL;
;       char* vT = vT0 + (ci & 1) * 40960;
;       {
.Lgs1_chunk:
	s_add_i32 s1, s54, -4
	s_cmp_lt_u32 s54, 4
	s_cselect_b32 s0, s54, s1
	s_movk_i32 s5, 0x1000
	s_cselect_b32 s1, 0x100, s5
	s_lshl_b32 s4, s35, 8
	s_add_u32 s4, s4, 0x8000
	s_lshl_b32 s5, s35, 12
	s_cmp_lt_u32 s54, 4
	s_cselect_b32 s4, s4, s5
	s_lshl_b32 s0, s0, 6
	s_sub_u32 s1, s1, 64
	s_sub_u32 s1, s1, s0
	s_cmp_eq_u32 s55, 0
	s_cselect_b32 s0, s0, s1
	s_add_u32 s0, s4, s0
	s_lshl_b32 s1, s0, 11
	s_add_u32 s20, s30, s1
	s_addc_u32 s21, s31, 0
	s_cmp_gt_u32 s54, 3
	s_cselect_b32 s96, 1, s60
	s_add_u32 s0, s97, s16
	s_cmp_eq_u32 s0, 0
	s_cbranch_scc1 .Lgs1_w29
	s_cmp_eq_u32 s0, 2
	s_cbranch_scc1 .Lgs1_w45
	s_waitcnt vmcnt(10)
	s_branch .Lgs1_waited

; __device__ __forceinline__ void gla_scan_phase(const Params& p, int j, bool need_ctx, char* smem, int tid, int bid) {
;     ...
;       {
;         if (tid < 128) ebend[tid] = ebv;
;         const int r = tid >> 3, c0 = tid & 7;
;         *(u32x4*)(qbL + swz256(r, c0)) = qx[0]; *(u32x4*)(qbL + swz256(r, c0 + 8)) = qx[1];
;         *(u32x4*)(kinvL + swz256(r, c0)) = kx[0]; *(u32x4*)(kinvL + swz256(r, c0 + 8)) = kx[1];
;         const int kdt = tid & 127, tgk = tid >> 7;
;         u32x4 w0 = {kt[0] | (kt[1] << 16), kt[2] | (kt[3] << 16), kt[4] | (kt[5] << 16), kt[6] | (kt[7] << 16)};
;         u32x4 w1 = {kt[8] | (kt[9] << 16), kt[10] | (kt[11] << 16), kt[12] | (kt[13] << 16), kt[14] | (kt[15] << 16)};
;         *(u32x4*)(kendT + swz128(kdt, tgk)) = w0;
;         *(u32x4*)(kendT + swz128(kdt, tgk + 4)) = w1;
;         u32x4 wv = {vv[0] | (vv[1] << 16), vv[2] | (vv[3] << 16), vv[4] | (vv[5] << 16), vv[6] | (vv[7] << 16)};
;         *(u32x4*)(vT + swz128(dvc, tg)) = wv;
;       }
.Lgs1_waited:
	ds_write_b128 v192, v[96:99]
	ds_write_b128 v193, v[100:103]
	ds_write_b128 v143, v[104:107] offset:16384
	ds_write_b128 v144, v[108:111] offset:16384
	ds_write_b128 v196, v[136:139]
	s_cmp_gt_u32 s81, 1
	s_cbranch_scc1 .Lgs1_noeb
	ds_write_b32 v197, v133
